# grid barrier: each block completes its L1 invalidate before publishing its arrival (instead of after the release); nothing is loaded between the two
# speedup vs baseline: 1.0924x; 1.0058x over previous
; __device__ __forceinline__ unsigned xb_ld(unsigned* p)              { return __hip_atomic_load(p, __ATOMIC_RELAXED, __HIP_MEMORY_SCOPE_AGENT); }
; __device__ __forceinline__ unsigned xb_add(unsigned* p, unsigned v) { return __hip_atomic_fetch_add(p, v, __ATOMIC_RELAXED, __HIP_MEMORY_SCOPE_AGENT); }
; #define XB_SPIN(cond, bar) do { unsigned _sp = 0; while (cond) { __builtin_amdgcn_s_sleep(1); \
;     if ((++_sp & 255u) == 0u) { if (xb_ld(&(bar)[XB_TMO])) break; if (_sp > XB_SPIN_CAP) { atomicAdd(&(bar)[XB_TMO], 1u); break; } } } } while (0)
; __device__ __forceinline__ void xcd_barrier(const XcdBarrier& b) {
;   asm volatile("s_waitcnt vmcnt(0)" ::: "memory");
;   __syncthreads();
;   if (threadIdx.x == 0) {
;     unsigned* bar = b.bar;
;     __builtin_amdgcn_s_waitcnt(0);
;     unsigned nloc = b.st[0], nx = b.st[1];
;     if (nloc == 0u) { xcd_barrier_complete(bar, b.x, nloc, nx); b.st[0] = nloc; b.st[1] = nx; }
;     const unsigned old = xb_add(&bar[XB_XSUB(b.x)], 1u);
;     const unsigned gen = old / nloc;
;     if (old + 1u == (gen + 1u) * nloc) {
;       __builtin_amdgcn_fence(__ATOMIC_RELEASE, "agent");
;       asm volatile("s_waitcnt vmcnt(0)" ::: "memory");
;       const unsigned og = xb_add(&bar[XB_TOP], 1u);
;       const unsigned tg = og / nx;
;       if (og + 1u == (tg + 1u) * nx) xb_add(&bar[XB_TOPGEN], 1u);
;       else XB_SPIN(xb_ld(&bar[XB_TOPGEN]) == tg, bar);
;       __builtin_amdgcn_fence(__ATOMIC_ACQUIRE, "agent");
;       xb_add(&bar[XB_XGEN(b.x)], 1u);
;       asm volatile("s_waitcnt vmcnt(0)" ::: "memory");
;     } else {
;       XB_SPIN(xb_ld(&bar[XB_XGEN(b.x)]) == gen, bar);
;       __builtin_amdgcn_fence(__ATOMIC_ACQUIRE, "agent");
;       asm volatile("s_waitcnt vmcnt(0)" ::: "memory");
;     }
.LBB0_55:
	s_waitcnt lgkmcnt(0)
	buffer_inv sc1
	s_waitcnt vmcnt(0)
	v_readfirstlane_b32 s2, v2
	v_readfirstlane_b32 s3, v0
	v_readlane_b32 s4, v240, 5
	s_lshl_b32 s4, s4, 8
	s_addk_i32 s4, 0x1400
	v_mov_b32_e32 v1, s4
	v_mov_b32_e32 v3, 1
	global_atomic_add v3, v1, v3, s[82:83] sc0
	s_mul_i32 s2, s2, 1
	s_mul_i32 s3, s3, 1
	s_and_b32 s4, s24, 15
	s_lshl_b32 s4, s4, 8
	s_addk_i32 s4, 0x2400
	s_waitcnt vmcnt(0)
	v_readfirstlane_b32 s5, v3
	s_add_i32 s5, s5, 1
	s_cmp_lg_u32 s5, s2
	s_cbranch_scc1 .Lxb0_nm
	buffer_wbl2 sc1
	s_waitcnt vmcnt(0)
	s_mov_b64 exec, 0xffff
	v_mbcnt_lo_u32_b32 v1, -1, 0
	v_lshlrev_b32_e32 v1, 8, v1
	v_add_u32_e32 v1, 0x2400, v1
	v_mov_b32_e32 v3, 1
	global_atomic_add v1, v3, s[82:83]
	s_mov_b64 exec, 1
	s_branch .Lxb0_wait
.Lxb0_nm:
.Lxb0_wait:
	v_mov_b32_e32 v1, s4
	s_mov_b32 s5, 0

; __device__ __forceinline__ unsigned xb_ld(unsigned* p)              { return __hip_atomic_load(p, __ATOMIC_RELAXED, __HIP_MEMORY_SCOPE_AGENT); }
; __device__ __forceinline__ unsigned xb_add(unsigned* p, unsigned v) { return __hip_atomic_fetch_add(p, v, __ATOMIC_RELAXED, __HIP_MEMORY_SCOPE_AGENT); }
; #define XB_SPIN(cond, bar) do { unsigned _sp = 0; while (cond) { __builtin_amdgcn_s_sleep(1); \
;     if ((++_sp & 255u) == 0u) { if (xb_ld(&(bar)[XB_TMO])) break; if (_sp > XB_SPIN_CAP) { atomicAdd(&(bar)[XB_TMO], 1u); break; } } } } while (0)
; __device__ __forceinline__ void xcd_barrier(const XcdBarrier& b) {
;   asm volatile("s_waitcnt vmcnt(0)" ::: "memory");
;   __syncthreads();
;   if (threadIdx.x == 0) {
;     unsigned* bar = b.bar;
;     __builtin_amdgcn_s_waitcnt(0);
;     unsigned nloc = b.st[0], nx = b.st[1];
;     if (nloc == 0u) { xcd_barrier_complete(bar, b.x, nloc, nx); b.st[0] = nloc; b.st[1] = nx; }
;     const unsigned old = xb_add(&bar[XB_XSUB(b.x)], 1u);
;     const unsigned gen = old / nloc;
;     if (old + 1u == (gen + 1u) * nloc) {
;       __builtin_amdgcn_fence(__ATOMIC_RELEASE, "agent");
;       asm volatile("s_waitcnt vmcnt(0)" ::: "memory");
;       const unsigned og = xb_add(&bar[XB_TOP], 1u);
;       const unsigned tg = og / nx;
;       if (og + 1u == (tg + 1u) * nx) xb_add(&bar[XB_TOPGEN], 1u);
;       else XB_SPIN(xb_ld(&bar[XB_TOPGEN]) == tg, bar);
;       __builtin_amdgcn_fence(__ATOMIC_ACQUIRE, "agent");
;       xb_add(&bar[XB_XGEN(b.x)], 1u);
;       asm volatile("s_waitcnt vmcnt(0)" ::: "memory");
;     } else {
;       XB_SPIN(xb_ld(&bar[XB_XGEN(b.x)]) == gen, bar);
;       __builtin_amdgcn_fence(__ATOMIC_ACQUIRE, "agent");
;       asm volatile("s_waitcnt vmcnt(0)" ::: "memory");
;     }
.LBB0_399:
	s_waitcnt lgkmcnt(0)
	buffer_inv sc1
	s_waitcnt vmcnt(0)
	v_readfirstlane_b32 s2, v2
	v_readfirstlane_b32 s3, v0
	v_readlane_b32 s4, v240, 5
	s_lshl_b32 s4, s4, 8
	s_addk_i32 s4, 0x1400
	v_mov_b32_e32 v1, s4
	v_mov_b32_e32 v3, 1
	global_atomic_add v3, v1, v3, s[82:83] sc0
	s_mul_i32 s2, s2, 2
	s_mul_i32 s3, s3, 2
	v_readlane_b32 s4, v240, 42
	s_and_b32 s4, s4, 15
	s_lshl_b32 s4, s4, 8
	s_addk_i32 s4, 0x2400
	s_waitcnt vmcnt(0)
	v_readfirstlane_b32 s5, v3
	s_add_i32 s5, s5, 1
	s_cmp_lg_u32 s5, s2
	s_cbranch_scc1 .Lxb1_nm
	buffer_wbl2 sc1
	s_waitcnt vmcnt(0)
	s_mov_b64 exec, 0xffff
	v_mbcnt_lo_u32_b32 v1, -1, 0
	v_lshlrev_b32_e32 v1, 8, v1
	v_add_u32_e32 v1, 0x2400, v1
	v_mov_b32_e32 v3, 1
	global_atomic_add v1, v3, s[82:83]
	s_mov_b64 exec, 1
	s_branch .Lxb1_wait

; __device__ __forceinline__ unsigned xb_ld(unsigned* p)              { return __hip_atomic_load(p, __ATOMIC_RELAXED, __HIP_MEMORY_SCOPE_AGENT); }
; __device__ __forceinline__ unsigned xb_add(unsigned* p, unsigned v) { return __hip_atomic_fetch_add(p, v, __ATOMIC_RELAXED, __HIP_MEMORY_SCOPE_AGENT); }
; #define XB_SPIN(cond, bar) do { unsigned _sp = 0; while (cond) { __builtin_amdgcn_s_sleep(1); \
;     if ((++_sp & 255u) == 0u) { if (xb_ld(&(bar)[XB_TMO])) break; if (_sp > XB_SPIN_CAP) { atomicAdd(&(bar)[XB_TMO], 1u); break; } } } } while (0)
; __device__ __forceinline__ void xcd_barrier(const XcdBarrier& b) {
;   asm volatile("s_waitcnt vmcnt(0)" ::: "memory");
;   __syncthreads();
;   if (threadIdx.x == 0) {
;     unsigned* bar = b.bar;
;     __builtin_amdgcn_s_waitcnt(0);
;     unsigned nloc = b.st[0], nx = b.st[1];
;     if (nloc == 0u) { xcd_barrier_complete(bar, b.x, nloc, nx); b.st[0] = nloc; b.st[1] = nx; }
;     const unsigned old = xb_add(&bar[XB_XSUB(b.x)], 1u);
;     const unsigned gen = old / nloc;
;     if (old + 1u == (gen + 1u) * nloc) {
;       __builtin_amdgcn_fence(__ATOMIC_RELEASE, "agent");
;       asm volatile("s_waitcnt vmcnt(0)" ::: "memory");
;       const unsigned og = xb_add(&bar[XB_TOP], 1u);
;       const unsigned tg = og / nx;
;       if (og + 1u == (tg + 1u) * nx) xb_add(&bar[XB_TOPGEN], 1u);
;       else XB_SPIN(xb_ld(&bar[XB_TOPGEN]) == tg, bar);
;       __builtin_amdgcn_fence(__ATOMIC_ACQUIRE, "agent");
;       xb_add(&bar[XB_XGEN(b.x)], 1u);
;       asm volatile("s_waitcnt vmcnt(0)" ::: "memory");
;     } else {
;       XB_SPIN(xb_ld(&bar[XB_XGEN(b.x)]) == gen, bar);
;       __builtin_amdgcn_fence(__ATOMIC_ACQUIRE, "agent");
;       asm volatile("s_waitcnt vmcnt(0)" ::: "memory");
;     }
.LBB0_507:
	s_waitcnt lgkmcnt(0)
	buffer_inv sc1
	s_waitcnt vmcnt(0)
	v_readfirstlane_b32 s2, v2
	v_readfirstlane_b32 s3, v0
	v_readlane_b32 s4, v240, 5
	s_lshl_b32 s4, s4, 8
	s_addk_i32 s4, 0x1400
	v_mov_b32_e32 v1, s4
	v_mov_b32_e32 v3, 1
	global_atomic_add v3, v1, v3, s[82:83] sc0
	s_mul_i32 s2, s2, 3
	s_mul_i32 s3, s3, 3
	v_readlane_b32 s4, v240, 42
	s_and_b32 s4, s4, 15
	s_lshl_b32 s4, s4, 8
	s_addk_i32 s4, 0x2400
	s_waitcnt vmcnt(0)
	v_readfirstlane_b32 s5, v3
	s_add_i32 s5, s5, 1
	s_cmp_lg_u32 s5, s2
	s_cbranch_scc1 .Lxb2_nm
	buffer_wbl2 sc1
	s_waitcnt vmcnt(0)
	s_mov_b64 exec, 0xffff
	v_mbcnt_lo_u32_b32 v1, -1, 0
	v_lshlrev_b32_e32 v1, 8, v1
	v_add_u32_e32 v1, 0x2400, v1
	v_mov_b32_e32 v3, 1
	global_atomic_add v1, v3, s[82:83]
	s_mov_b64 exec, 1
	s_branch .Lxb2_wait

; #define LAS __attribute__((address_space(3)))
; __device__ __forceinline__ unsigned xb_ld(unsigned* p)              { return __hip_atomic_load(p, __ATOMIC_RELAXED, __HIP_MEMORY_SCOPE_AGENT); }
; __device__ __forceinline__ unsigned xb_add(unsigned* p, unsigned v) { return __hip_atomic_fetch_add(p, v, __ATOMIC_RELAXED, __HIP_MEMORY_SCOPE_AGENT); }
; __device__ __forceinline__ unsigned xb_xcc_id() { return (unsigned)__builtin_amdgcn_s_getreg((3 << 11) | 20) & 0xFu; }
; #define XB_SPIN(cond, bar) do { unsigned _sp = 0; while (cond) { __builtin_amdgcn_s_sleep(1); \
;     if ((++_sp & 255u) == 0u) { if (xb_ld(&(bar)[XB_TMO])) break; if (_sp > XB_SPIN_CAP) { atomicAdd(&(bar)[XB_TMO], 1u); break; } } } } while (0)
; __device__ __forceinline__ void xcd_barrier(const XcdBarrier& b) {
;   asm volatile("s_waitcnt vmcnt(0)" ::: "memory");
;   __syncthreads();
;   if (threadIdx.x == 0) {
;     unsigned* bar = b.bar;
;     __builtin_amdgcn_s_waitcnt(0);
;     unsigned nloc = b.st[0], nx = b.st[1];
;     if (nloc == 0u) { xcd_barrier_complete(bar, b.x, nloc, nx); b.st[0] = nloc; b.st[1] = nx; }
;     const unsigned old = xb_add(&bar[XB_XSUB(b.x)], 1u);
;     const unsigned gen = old / nloc;
;     if (old + 1u == (gen + 1u) * nloc) {
;       __builtin_amdgcn_fence(__ATOMIC_RELEASE, "agent");
;       asm volatile("s_waitcnt vmcnt(0)" ::: "memory");
;       const unsigned og = xb_add(&bar[XB_TOP], 1u);
;       const unsigned tg = og / nx;
;       if (og + 1u == (tg + 1u) * nx) xb_add(&bar[XB_TOPGEN], 1u);
;       else XB_SPIN(xb_ld(&bar[XB_TOPGEN]) == tg, bar);
;       __builtin_amdgcn_fence(__ATOMIC_ACQUIRE, "agent");
;       xb_add(&bar[XB_XGEN(b.x)], 1u);
;       asm volatile("s_waitcnt vmcnt(0)" ::: "memory");
;     } else {
;       XB_SPIN(xb_ld(&bar[XB_XGEN(b.x)]) == gen, bar);
;       __builtin_amdgcn_fence(__ATOMIC_ACQUIRE, "agent");
;       asm volatile("s_waitcnt vmcnt(0)" ::: "memory");
;     }
;   }
;   __syncthreads();
; }
; __device__ void mid_barrier(const Params& p, char* smem) {
;   XcdBarrier b; b.bar = p.bar; b.x = xb_xcc_id(); b.st = (volatile LAS unsigned*)(smem + 2 * GEMM_SMEM + 768);
;   xcd_barrier(b);
; }
.LBB0_723:
	s_waitcnt lgkmcnt(0)
	buffer_inv sc1
	s_waitcnt vmcnt(0)
	v_readfirstlane_b32 s0, v114
	v_readfirstlane_b32 s2, v112
	v_readlane_b32 s3, v240, 5
	s_lshl_b32 s3, s3, 8
	s_addk_i32 s3, 0x1400
	v_mov_b32_e32 v113, s3
	v_mov_b32_e32 v115, 1
	global_atomic_add v115, v113, v115, s[82:83] sc0
	s_mul_i32 s0, s0, 4
	s_mul_i32 s2, s2, 4
	v_readlane_b32 s3, v240, 42
	s_and_b32 s3, s3, 15
	s_lshl_b32 s3, s3, 8
	s_addk_i32 s3, 0x2400
	s_waitcnt vmcnt(0)
	v_readfirstlane_b32 s6, v115
	s_add_i32 s6, s6, 1
	s_cmp_lg_u32 s6, s0
	s_cbranch_scc1 .Lxb3_nm
	buffer_wbl2 sc1
	s_waitcnt vmcnt(0)
	s_mov_b64 exec, 0xffff
	v_mbcnt_lo_u32_b32 v113, -1, 0
	v_lshlrev_b32_e32 v113, 8, v113
	v_add_u32_e32 v113, 0x2400, v113
	v_mov_b32_e32 v115, 1
	global_atomic_add v113, v115, s[82:83]
	s_mov_b64 exec, 1
	s_branch .Lxb3_wait
.Lxb3_nm:
.Lxb3_wait:
	v_mov_b32_e32 v113, s3
	s_mov_b32 s6, 0

; __device__ __forceinline__ unsigned xb_ld(unsigned* p)              { return __hip_atomic_load(p, __ATOMIC_RELAXED, __HIP_MEMORY_SCOPE_AGENT); }
; __device__ __forceinline__ unsigned xb_add(unsigned* p, unsigned v) { return __hip_atomic_fetch_add(p, v, __ATOMIC_RELAXED, __HIP_MEMORY_SCOPE_AGENT); }
; #define XB_SPIN(cond, bar) do { unsigned _sp = 0; while (cond) { __builtin_amdgcn_s_sleep(1); \
;     if ((++_sp & 255u) == 0u) { if (xb_ld(&(bar)[XB_TMO])) break; if (_sp > XB_SPIN_CAP) { atomicAdd(&(bar)[XB_TMO], 1u); break; } } } } while (0)
; __device__ __forceinline__ void xcd_barrier(const XcdBarrier& b) {
;   asm volatile("s_waitcnt vmcnt(0)" ::: "memory");
;   __syncthreads();
;   if (threadIdx.x == 0) {
;     unsigned* bar = b.bar;
;     __builtin_amdgcn_s_waitcnt(0);
;     unsigned nloc = b.st[0], nx = b.st[1];
;     if (nloc == 0u) { xcd_barrier_complete(bar, b.x, nloc, nx); b.st[0] = nloc; b.st[1] = nx; }
;     const unsigned old = xb_add(&bar[XB_XSUB(b.x)], 1u);
;     const unsigned gen = old / nloc;
;     if (old + 1u == (gen + 1u) * nloc) {
;       __builtin_amdgcn_fence(__ATOMIC_RELEASE, "agent");
;       asm volatile("s_waitcnt vmcnt(0)" ::: "memory");
;       const unsigned og = xb_add(&bar[XB_TOP], 1u);
;       const unsigned tg = og / nx;
;       if (og + 1u == (tg + 1u) * nx) xb_add(&bar[XB_TOPGEN], 1u);
;       else XB_SPIN(xb_ld(&bar[XB_TOPGEN]) == tg, bar);
;       __builtin_amdgcn_fence(__ATOMIC_ACQUIRE, "agent");
;       xb_add(&bar[XB_XGEN(b.x)], 1u);
;       asm volatile("s_waitcnt vmcnt(0)" ::: "memory");
;     } else {
;       XB_SPIN(xb_ld(&bar[XB_XGEN(b.x)]) == gen, bar);
;       __builtin_amdgcn_fence(__ATOMIC_ACQUIRE, "agent");
;       asm volatile("s_waitcnt vmcnt(0)" ::: "memory");
;     }
.LBB0_853:
	s_waitcnt lgkmcnt(0)
	buffer_inv sc1
	s_waitcnt vmcnt(0)
	v_readfirstlane_b32 s2, v2
	v_readfirstlane_b32 s3, v0
	v_readlane_b32 s4, v240, 5
	s_lshl_b32 s4, s4, 8
	s_addk_i32 s4, 0x1400
	v_mov_b32_e32 v1, s4
	v_mov_b32_e32 v3, 1
	global_atomic_add v3, v1, v3, s[82:83] sc0
	s_mul_i32 s2, s2, 4
	s_mul_i32 s3, s3, 4
	v_readlane_b32 s4, v240, 42
	s_and_b32 s4, s4, 15
	s_lshl_b32 s4, s4, 8
	s_addk_i32 s4, 0x2400
	s_waitcnt vmcnt(0)
	v_readfirstlane_b32 s5, v3
	s_add_i32 s5, s5, 1
	s_cmp_lg_u32 s5, s2
	s_cbranch_scc1 .Lxb4_nm
	buffer_wbl2 sc1
	s_waitcnt vmcnt(0)
	s_mov_b64 exec, 0xffff
	v_mbcnt_lo_u32_b32 v1, -1, 0
	v_lshlrev_b32_e32 v1, 8, v1
	v_add_u32_e32 v1, 0x2400, v1
	v_mov_b32_e32 v3, 1
	global_atomic_add v1, v3, s[82:83]
	s_mov_b64 exec, 1
	s_branch .Lxb4_wait

; __device__ __forceinline__ unsigned xb_ld(unsigned* p)              { return __hip_atomic_load(p, __ATOMIC_RELAXED, __HIP_MEMORY_SCOPE_AGENT); }
; __device__ __forceinline__ unsigned xb_add(unsigned* p, unsigned v) { return __hip_atomic_fetch_add(p, v, __ATOMIC_RELAXED, __HIP_MEMORY_SCOPE_AGENT); }
; #define XB_SPIN(cond, bar) do { unsigned _sp = 0; while (cond) { __builtin_amdgcn_s_sleep(1); \
;     if ((++_sp & 255u) == 0u) { if (xb_ld(&(bar)[XB_TMO])) break; if (_sp > XB_SPIN_CAP) { atomicAdd(&(bar)[XB_TMO], 1u); break; } } } } while (0)
; __device__ __forceinline__ void xcd_barrier(const XcdBarrier& b) {
;   asm volatile("s_waitcnt vmcnt(0)" ::: "memory");
;   __syncthreads();
;   if (threadIdx.x == 0) {
;     unsigned* bar = b.bar;
;     __builtin_amdgcn_s_waitcnt(0);
;     unsigned nloc = b.st[0], nx = b.st[1];
;     if (nloc == 0u) { xcd_barrier_complete(bar, b.x, nloc, nx); b.st[0] = nloc; b.st[1] = nx; }
;     const unsigned old = xb_add(&bar[XB_XSUB(b.x)], 1u);
;     const unsigned gen = old / nloc;
;     if (old + 1u == (gen + 1u) * nloc) {
;       __builtin_amdgcn_fence(__ATOMIC_RELEASE, "agent");
;       asm volatile("s_waitcnt vmcnt(0)" ::: "memory");
;       const unsigned og = xb_add(&bar[XB_TOP], 1u);
;       const unsigned tg = og / nx;
;       if (og + 1u == (tg + 1u) * nx) xb_add(&bar[XB_TOPGEN], 1u);
;       else XB_SPIN(xb_ld(&bar[XB_TOPGEN]) == tg, bar);
;       __builtin_amdgcn_fence(__ATOMIC_ACQUIRE, "agent");
;       xb_add(&bar[XB_XGEN(b.x)], 1u);
;       asm volatile("s_waitcnt vmcnt(0)" ::: "memory");
;     } else {
;       XB_SPIN(xb_ld(&bar[XB_XGEN(b.x)]) == gen, bar);
;       __builtin_amdgcn_fence(__ATOMIC_ACQUIRE, "agent");
;       asm volatile("s_waitcnt vmcnt(0)" ::: "memory");
;     }
.LBB0_987:
	s_waitcnt lgkmcnt(0)
	buffer_inv sc1
	s_waitcnt vmcnt(0)
	v_readfirstlane_b32 s2, v2
	v_readfirstlane_b32 s3, v0
	v_readlane_b32 s4, v240, 5
	s_lshl_b32 s4, s4, 8
	s_addk_i32 s4, 0x1400
	v_mov_b32_e32 v1, s4
	v_mov_b32_e32 v3, 1
	global_atomic_add v3, v1, v3, s[82:83] sc0
	s_mul_i32 s2, s2, 5
	s_mul_i32 s3, s3, 5
	v_readlane_b32 s4, v240, 42
	s_and_b32 s4, s4, 15
	s_lshl_b32 s4, s4, 8
	s_addk_i32 s4, 0x2400
	s_waitcnt vmcnt(0)
	v_readfirstlane_b32 s5, v3
	s_add_i32 s5, s5, 1
	s_cmp_lg_u32 s5, s2
	s_cbranch_scc1 .Lxb6_nm
	buffer_wbl2 sc1
	s_waitcnt vmcnt(0)
	s_mov_b64 exec, 0xffff
	v_mbcnt_lo_u32_b32 v1, -1, 0
	v_lshlrev_b32_e32 v1, 8, v1
	v_add_u32_e32 v1, 0x2400, v1
	v_mov_b32_e32 v3, 1
	global_atomic_add v1, v3, s[82:83]
	s_mov_b64 exec, 1
	s_branch .Lxb6_wait

; __device__ __forceinline__ unsigned xb_ld(unsigned* p)              { return __hip_atomic_load(p, __ATOMIC_RELAXED, __HIP_MEMORY_SCOPE_AGENT); }
; __device__ __forceinline__ unsigned xb_add(unsigned* p, unsigned v) { return __hip_atomic_fetch_add(p, v, __ATOMIC_RELAXED, __HIP_MEMORY_SCOPE_AGENT); }
; #define XB_SPIN(cond, bar) do { unsigned _sp = 0; while (cond) { __builtin_amdgcn_s_sleep(1); \
;     if ((++_sp & 255u) == 0u) { if (xb_ld(&(bar)[XB_TMO])) break; if (_sp > XB_SPIN_CAP) { atomicAdd(&(bar)[XB_TMO], 1u); break; } } } } while (0)
; __device__ __forceinline__ void xcd_barrier(const XcdBarrier& b) {
;   asm volatile("s_waitcnt vmcnt(0)" ::: "memory");
;   __syncthreads();
;   if (threadIdx.x == 0) {
;     unsigned* bar = b.bar;
;     __builtin_amdgcn_s_waitcnt(0);
;     unsigned nloc = b.st[0], nx = b.st[1];
;     if (nloc == 0u) { xcd_barrier_complete(bar, b.x, nloc, nx); b.st[0] = nloc; b.st[1] = nx; }
;     const unsigned old = xb_add(&bar[XB_XSUB(b.x)], 1u);
;     const unsigned gen = old / nloc;
;     if (old + 1u == (gen + 1u) * nloc) {
;       __builtin_amdgcn_fence(__ATOMIC_RELEASE, "agent");
;       asm volatile("s_waitcnt vmcnt(0)" ::: "memory");
;       const unsigned og = xb_add(&bar[XB_TOP], 1u);
;       const unsigned tg = og / nx;
;       if (og + 1u == (tg + 1u) * nx) xb_add(&bar[XB_TOPGEN], 1u);
;       else XB_SPIN(xb_ld(&bar[XB_TOPGEN]) == tg, bar);
;       __builtin_amdgcn_fence(__ATOMIC_ACQUIRE, "agent");
;       xb_add(&bar[XB_XGEN(b.x)], 1u);
;       asm volatile("s_waitcnt vmcnt(0)" ::: "memory");
;     } else {
;       XB_SPIN(xb_ld(&bar[XB_XGEN(b.x)]) == gen, bar);
;       __builtin_amdgcn_fence(__ATOMIC_ACQUIRE, "agent");
;       asm volatile("s_waitcnt vmcnt(0)" ::: "memory");
;     }
.LBB0_1125:
	s_waitcnt lgkmcnt(0)
	buffer_inv sc1
	s_waitcnt vmcnt(0)
	v_readfirstlane_b32 s2, v2
	v_readfirstlane_b32 s3, v0
	v_readlane_b32 s4, v240, 5
	s_lshl_b32 s4, s4, 8
	s_addk_i32 s4, 0x1400
	v_mov_b32_e32 v1, s4
	v_mov_b32_e32 v3, 1
	global_atomic_add v3, v1, v3, s[82:83] sc0
	s_mul_i32 s2, s2, 6
	s_mul_i32 s3, s3, 6
	v_readlane_b32 s4, v240, 42
	s_and_b32 s4, s4, 15
	s_lshl_b32 s4, s4, 8
	s_addk_i32 s4, 0x2400
	s_waitcnt vmcnt(0)
	v_readfirstlane_b32 s5, v3
	s_add_i32 s5, s5, 1
	s_cmp_lg_u32 s5, s2
	s_cbranch_scc1 .Lxb7_nm
	buffer_wbl2 sc1
	s_waitcnt vmcnt(0)
	s_mov_b64 exec, 0xffff
	v_mbcnt_lo_u32_b32 v1, -1, 0
	v_lshlrev_b32_e32 v1, 8, v1
	v_add_u32_e32 v1, 0x2400, v1
	v_mov_b32_e32 v3, 1
	global_atomic_add v1, v3, s[82:83]
	s_mov_b64 exec, 1
	s_branch .Lxb7_wait

; __device__ __forceinline__ unsigned xb_ld(unsigned* p)              { return __hip_atomic_load(p, __ATOMIC_RELAXED, __HIP_MEMORY_SCOPE_AGENT); }
; __device__ __forceinline__ unsigned xb_add(unsigned* p, unsigned v) { return __hip_atomic_fetch_add(p, v, __ATOMIC_RELAXED, __HIP_MEMORY_SCOPE_AGENT); }
; #define XB_SPIN(cond, bar) do { unsigned _sp = 0; while (cond) { __builtin_amdgcn_s_sleep(1); \
;     if ((++_sp & 255u) == 0u) { if (xb_ld(&(bar)[XB_TMO])) break; if (_sp > XB_SPIN_CAP) { atomicAdd(&(bar)[XB_TMO], 1u); break; } } } } while (0)
; __device__ __forceinline__ void xcd_barrier(const XcdBarrier& b) {
;   asm volatile("s_waitcnt vmcnt(0)" ::: "memory");
;   __syncthreads();
;   if (threadIdx.x == 0) {
;     unsigned* bar = b.bar;
;     __builtin_amdgcn_s_waitcnt(0);
;     unsigned nloc = b.st[0], nx = b.st[1];
;     if (nloc == 0u) { xcd_barrier_complete(bar, b.x, nloc, nx); b.st[0] = nloc; b.st[1] = nx; }
;     const unsigned old = xb_add(&bar[XB_XSUB(b.x)], 1u);
;     const unsigned gen = old / nloc;
;     if (old + 1u == (gen + 1u) * nloc) {
;       __builtin_amdgcn_fence(__ATOMIC_RELEASE, "agent");
;       asm volatile("s_waitcnt vmcnt(0)" ::: "memory");
;       const unsigned og = xb_add(&bar[XB_TOP], 1u);
;       const unsigned tg = og / nx;
;       if (og + 1u == (tg + 1u) * nx) xb_add(&bar[XB_TOPGEN], 1u);
;       else XB_SPIN(xb_ld(&bar[XB_TOPGEN]) == tg, bar);
;       __builtin_amdgcn_fence(__ATOMIC_ACQUIRE, "agent");
;       xb_add(&bar[XB_XGEN(b.x)], 1u);
;       asm volatile("s_waitcnt vmcnt(0)" ::: "memory");
;     } else {
;       XB_SPIN(xb_ld(&bar[XB_XGEN(b.x)]) == gen, bar);
;       __builtin_amdgcn_fence(__ATOMIC_ACQUIRE, "agent");
;       asm volatile("s_waitcnt vmcnt(0)" ::: "memory");
;     }
.LBB0_1224:
	s_waitcnt lgkmcnt(0)
	buffer_inv sc1
	s_waitcnt vmcnt(0)
	v_readfirstlane_b32 s2, v2
	v_readfirstlane_b32 s3, v0
	v_readlane_b32 s4, v240, 5
	s_lshl_b32 s4, s4, 8
	s_addk_i32 s4, 0x1400
	v_mov_b32_e32 v1, s4
	v_mov_b32_e32 v3, 1
	global_atomic_add v3, v1, v3, s[82:83] sc0
	s_mul_i32 s2, s2, 7
	s_mul_i32 s3, s3, 7
	v_readlane_b32 s4, v240, 42
	s_and_b32 s4, s4, 15
	s_lshl_b32 s4, s4, 8
	s_addk_i32 s4, 0x2400
	s_waitcnt vmcnt(0)
	v_readfirstlane_b32 s5, v3
	s_add_i32 s5, s5, 1
	s_cmp_lg_u32 s5, s2
	s_cbranch_scc1 .Lxb8_nm
	buffer_wbl2 sc1
	s_waitcnt vmcnt(0)
	s_mov_b64 exec, 0xffff
	v_mbcnt_lo_u32_b32 v1, -1, 0
	v_lshlrev_b32_e32 v1, 8, v1
	v_add_u32_e32 v1, 0x2400, v1
	v_mov_b32_e32 v3, 1
	global_atomic_add v1, v3, s[82:83]
	s_mov_b64 exec, 1
	s_branch .Lxb8_wait

; __device__ __forceinline__ unsigned xb_ld(unsigned* p)              { return __hip_atomic_load(p, __ATOMIC_RELAXED, __HIP_MEMORY_SCOPE_AGENT); }
; __device__ __forceinline__ unsigned xb_add(unsigned* p, unsigned v) { return __hip_atomic_fetch_add(p, v, __ATOMIC_RELAXED, __HIP_MEMORY_SCOPE_AGENT); }
; #define XB_SPIN(cond, bar) do { unsigned _sp = 0; while (cond) { __builtin_amdgcn_s_sleep(1); \
;     if ((++_sp & 255u) == 0u) { if (xb_ld(&(bar)[XB_TMO])) break; if (_sp > XB_SPIN_CAP) { atomicAdd(&(bar)[XB_TMO], 1u); break; } } } } while (0)
; __device__ __forceinline__ void xcd_barrier(const XcdBarrier& b) {
;   asm volatile("s_waitcnt vmcnt(0)" ::: "memory");
;   __syncthreads();
;   if (threadIdx.x == 0) {
;     unsigned* bar = b.bar;
;     __builtin_amdgcn_s_waitcnt(0);
;     unsigned nloc = b.st[0], nx = b.st[1];
;     if (nloc == 0u) { xcd_barrier_complete(bar, b.x, nloc, nx); b.st[0] = nloc; b.st[1] = nx; }
;     const unsigned old = xb_add(&bar[XB_XSUB(b.x)], 1u);
;     const unsigned gen = old / nloc;
;     if (old + 1u == (gen + 1u) * nloc) {
;       __builtin_amdgcn_fence(__ATOMIC_RELEASE, "agent");
;       asm volatile("s_waitcnt vmcnt(0)" ::: "memory");
;       const unsigned og = xb_add(&bar[XB_TOP], 1u);
;       const unsigned tg = og / nx;
;       if (og + 1u == (tg + 1u) * nx) xb_add(&bar[XB_TOPGEN], 1u);
;       else XB_SPIN(xb_ld(&bar[XB_TOPGEN]) == tg, bar);
;       __builtin_amdgcn_fence(__ATOMIC_ACQUIRE, "agent");
;       xb_add(&bar[XB_XGEN(b.x)], 1u);
;       asm volatile("s_waitcnt vmcnt(0)" ::: "memory");
;     } else {
;       XB_SPIN(xb_ld(&bar[XB_XGEN(b.x)]) == gen, bar);
;       __builtin_amdgcn_fence(__ATOMIC_ACQUIRE, "agent");
;       asm volatile("s_waitcnt vmcnt(0)" ::: "memory");
;     }
.LBB0_1306:
	s_waitcnt lgkmcnt(0)
	buffer_inv sc1
	s_waitcnt vmcnt(0)
	v_readfirstlane_b32 s2, v2
	v_readfirstlane_b32 s3, v0
	v_readlane_b32 s4, v240, 5
	s_lshl_b32 s4, s4, 8
	s_addk_i32 s4, 0x1400
	v_mov_b32_e32 v1, s4
	v_mov_b32_e32 v3, 1
	global_atomic_add v3, v1, v3, s[82:83] sc0
	s_mul_i32 s2, s2, 8
	s_mul_i32 s3, s3, 8
	v_readlane_b32 s4, v240, 42
	s_and_b32 s4, s4, 15
	s_lshl_b32 s4, s4, 8
	s_addk_i32 s4, 0x2400
	s_waitcnt vmcnt(0)
	v_readfirstlane_b32 s5, v3
	s_add_i32 s5, s5, 1
	s_cmp_lg_u32 s5, s2
	s_cbranch_scc1 .Lxb9_nm
	buffer_wbl2 sc1
	s_waitcnt vmcnt(0)
	s_mov_b64 exec, 0xffff
	v_mbcnt_lo_u32_b32 v1, -1, 0
	v_lshlrev_b32_e32 v1, 8, v1
	v_add_u32_e32 v1, 0x2400, v1
	v_mov_b32_e32 v3, 1
	global_atomic_add v1, v3, s[82:83]
	s_mov_b64 exec, 1
	s_branch .Lxb9_wait

; __device__ __forceinline__ unsigned xb_ld(unsigned* p)              { return __hip_atomic_load(p, __ATOMIC_RELAXED, __HIP_MEMORY_SCOPE_AGENT); }
; __device__ __forceinline__ unsigned xb_add(unsigned* p, unsigned v) { return __hip_atomic_fetch_add(p, v, __ATOMIC_RELAXED, __HIP_MEMORY_SCOPE_AGENT); }
; #define XB_SPIN(cond, bar) do { unsigned _sp = 0; while (cond) { __builtin_amdgcn_s_sleep(1); \
;     if ((++_sp & 255u) == 0u) { if (xb_ld(&(bar)[XB_TMO])) break; if (_sp > XB_SPIN_CAP) { atomicAdd(&(bar)[XB_TMO], 1u); break; } } } } while (0)
; __device__ __forceinline__ void xcd_barrier(const XcdBarrier& b) {
;   asm volatile("s_waitcnt vmcnt(0)" ::: "memory");
;   __syncthreads();
;   if (threadIdx.x == 0) {
;     unsigned* bar = b.bar;
;     __builtin_amdgcn_s_waitcnt(0);
;     unsigned nloc = b.st[0], nx = b.st[1];
;     if (nloc == 0u) { xcd_barrier_complete(bar, b.x, nloc, nx); b.st[0] = nloc; b.st[1] = nx; }
;     const unsigned old = xb_add(&bar[XB_XSUB(b.x)], 1u);
;     const unsigned gen = old / nloc;
;     if (old + 1u == (gen + 1u) * nloc) {
;       __builtin_amdgcn_fence(__ATOMIC_RELEASE, "agent");
;       asm volatile("s_waitcnt vmcnt(0)" ::: "memory");
;       const unsigned og = xb_add(&bar[XB_TOP], 1u);
;       const unsigned tg = og / nx;
;       if (og + 1u == (tg + 1u) * nx) xb_add(&bar[XB_TOPGEN], 1u);
;       else XB_SPIN(xb_ld(&bar[XB_TOPGEN]) == tg, bar);
;       __builtin_amdgcn_fence(__ATOMIC_ACQUIRE, "agent");
;       xb_add(&bar[XB_XGEN(b.x)], 1u);
;       asm volatile("s_waitcnt vmcnt(0)" ::: "memory");
;     } else {
;       XB_SPIN(xb_ld(&bar[XB_XGEN(b.x)]) == gen, bar);
;       __builtin_amdgcn_fence(__ATOMIC_ACQUIRE, "agent");
;       asm volatile("s_waitcnt vmcnt(0)" ::: "memory");
;     }
.LBB0_1388:
	s_waitcnt lgkmcnt(0)
	buffer_inv sc1
	s_waitcnt vmcnt(0)
	v_readfirstlane_b32 s2, v2
	v_readfirstlane_b32 s3, v0
	v_readlane_b32 s4, v240, 5
	s_lshl_b32 s4, s4, 8
	s_addk_i32 s4, 0x1400
	v_mov_b32_e32 v1, s4
	v_mov_b32_e32 v3, 1
	global_atomic_add v3, v1, v3, s[82:83] sc0
	s_mul_i32 s2, s2, 9
	s_mul_i32 s3, s3, 9
	v_readlane_b32 s4, v240, 42
	s_and_b32 s4, s4, 15
	s_lshl_b32 s4, s4, 8
	s_addk_i32 s4, 0x2400
	s_waitcnt vmcnt(0)
	v_readfirstlane_b32 s5, v3
	s_add_i32 s5, s5, 1
	s_cmp_lg_u32 s5, s2
	s_cbranch_scc1 .Lxb10_nm
	buffer_wbl2 sc1
	s_waitcnt vmcnt(0)
	s_mov_b64 exec, 0xffff
	v_mbcnt_lo_u32_b32 v1, -1, 0
	v_lshlrev_b32_e32 v1, 8, v1
	v_add_u32_e32 v1, 0x2400, v1
	v_mov_b32_e32 v3, 1
	global_atomic_add v1, v3, s[82:83]
	s_mov_b64 exec, 1
	s_branch .Lxb10_wait
